# v25 + rwkv_post output units: group-norm weight/bias vectors of units 2-4 loaded up front into spare registers (counted waits skip the unit's store)
# baseline (speedup 1.0000x reference)
; #define LAS __attribute__((address_space(3)))
; DI f32x4 mma16(bf16x8 a, bf16x8 b, f32x4 c) { return __builtin_amdgcn_mfma_f32_16x16x32_bf16(a, b, c, 0, 0, 0); }
; DI void rwkv_post_item(KA a, const int l, LAS unsigned char* lds, const int tile) {
;     ...
;     const int hd = w >> 1, th = w & 1;
;     f32x4 accg[4][2];
; #pragma unroll
;     for (int ct = 0; ct < 4; ++ct) { accg[ct][0] = ZERO4; accg[ct][1] = ZERO4; }
;     const bf16* g2T = (const bf16*)(ws + WS_SMALL + l * SMALL_STRIDE + SM_G2T);
; #pragma unroll
;     for (int ks = 0; ks < 5; ++ks) {
;         bf16x8 af[2];
; #pragma unroll
;         for (int rt = 0; rt < 2; ++rt) af[rt] = *(const LAS bf16x8*)(Ag + (32 * th + 16 * rt + fr) * PG + ks * 32 + fq * 8);
; #pragma unroll
;         for (int ct = 0; ct < 4; ++ct) { const bf16x8 bg = *(const bf16x8*)(g2T + (size_t)(hd * 64 + ct * 16 + fr) * 192 + ks * 32 + fq * 8);
; #pragma unroll
;             for (int rt = 0; rt < 2; ++rt) accg[ct][rt] = mma16(bg, af[rt], accg[ct][rt]); }
;     }
.LBB0_980:
	s_or_b64 exec, exec, s[6:7]
	v_and_b32_e32 v0, 15, v5
	v_readlane_b32 s6, v254, 32
	v_lshrrev_b32_e32 v1, 1, v5
	v_bfe_u32 v60, v5, 4, 2
	s_add_u32 s6, s4, s6
	v_and_or_b32 v61, v1, 32, v0
	v_ashrrev_i32_e32 v1, 1, v5
	s_addc_u32 s7, s5, 0
	v_lshlrev_b32_e32 v192, 4, v60
	v_and_b32_e32 v62, 0xffffffc0, v1
	v_or_b32_e32 v34, v62, v0
	v_lshl_add_u64 v[0:1], s[6:7], 0, v[192:193]
	s_mov_b64 s[6:7], 0x310000
	v_lshl_add_u64 v[32:33], v[0:1], 0, s[6:7]
	s_movk_i32 s8, 0x180
	v_mul_u32_u24_e32 v0, 0x150, v61
	v_mad_i64_i32 v[52:53], s[6:7], v34, s8, v[32:33]
	v_or_b32_e32 v16, 16, v34
	v_or_b32_e32 v24, 32, v34
	v_or_b32_e32 v34, 48, v34
	v_add3_u32 v48, 0, v192, v0
	v_mad_i64_i32 v[54:55], s[6:7], v16, s8, v[32:33]
	v_mad_i64_i32 v[56:57], s[6:7], v24, s8, v[32:33]
	v_mad_i64_i32 v[58:59], s[6:7], v34, s8, v[32:33]
	s_waitcnt lgkmcnt(0)
	s_barrier
	ds_read_b128 v[0:3], v48
	ds_read_b128 v[4:7], v48 offset:5376
	global_load_dwordx4 v[8:11], v[52:53], off
	global_load_dwordx4 v[16:19], v[54:55], off
	global_load_dwordx4 v[24:27], v[56:57], off
	global_load_dwordx4 v[32:35], v[58:59], off
	global_load_dwordx4 v[120:123], v[52:53], off offset:64
	global_load_dwordx4 v[124:127], v[54:55], off offset:64
	global_load_dwordx4 v[128:131], v[56:57], off offset:64
	global_load_dwordx4 v[132:135], v[58:59], off offset:64
	global_load_dwordx4 v[136:139], v[52:53], off offset:128
	global_load_dwordx4 v[140:143], v[54:55], off offset:128
	global_load_dwordx4 v[144:147], v[56:57], off offset:128
	global_load_dwordx4 v[148:151], v[58:59], off offset:128
	global_load_dwordx4 v[152:155], v[52:53], off offset:192
	global_load_dwordx4 v[156:159], v[54:55], off offset:192
	global_load_dwordx4 v[160:163], v[56:57], off offset:192
	global_load_dwordx4 v[164:167], v[58:59], off offset:192
	global_load_dwordx4 v[168:171], v[52:53], off offset:256
	global_load_dwordx4 v[172:175], v[54:55], off offset:256
	global_load_dwordx4 v[176:179], v[56:57], off offset:256
	global_load_dwordx4 v[180:183], v[58:59], off offset:256
	s_add_u32 s10, s4, 0x18000000
	s_addc_u32 s11, s5, 0
	s_add_u32 s8, s4, 0x19000000
	s_addc_u32 s9, s5, 0
	v_readlane_b32 s16, v254, 33
	s_add_u32 s6, s4, 0x1a000000
	v_readlane_b32 s17, v254, 34
	s_addc_u32 s7, s5, 0
	s_lshl_b64 s[22:23], s[16:17], 2
	s_waitcnt vmcnt(19) lgkmcnt(1)
	v_mfma_f32_16x16x32_bf16 v[12:15], v[8:11], v[0:3], 0
	s_waitcnt lgkmcnt(0)
	v_mfma_f32_16x16x32_bf16 v[8:11], v[8:11], v[4:7], 0
	s_waitcnt vmcnt(18)
	v_mfma_f32_16x16x32_bf16 v[20:23], v[16:19], v[0:3], 0
	v_mfma_f32_16x16x32_bf16 v[16:19], v[16:19], v[4:7], 0
	s_waitcnt vmcnt(17)
	v_mfma_f32_16x16x32_bf16 v[28:31], v[24:27], v[0:3], 0
	v_mfma_f32_16x16x32_bf16 v[24:27], v[24:27], v[4:7], 0
	s_waitcnt vmcnt(16)
	v_mfma_f32_16x16x32_bf16 v[0:3], v[32:35], v[0:3], 0
	v_mfma_f32_16x16x32_bf16 v[4:7], v[32:35], v[4:7], 0
	ds_read_b128 v[32:35], v48 offset:64
	ds_read_b128 v[36:39], v48 offset:5440
	s_waitcnt vmcnt(0) lgkmcnt(1)
	v_mfma_f32_16x16x32_bf16 v[12:15], v[120:123], v[32:35], v[12:15]
	s_waitcnt lgkmcnt(0)
	v_mfma_f32_16x16x32_bf16 v[8:11], v[120:123], v[36:39], v[8:11]
	v_mfma_f32_16x16x32_bf16 v[20:23], v[124:127], v[32:35], v[20:23]
	v_mfma_f32_16x16x32_bf16 v[16:19], v[124:127], v[36:39], v[16:19]
	v_mfma_f32_16x16x32_bf16 v[28:31], v[128:131], v[32:35], v[28:31]
	v_mfma_f32_16x16x32_bf16 v[24:27], v[128:131], v[36:39], v[24:27]
	v_mfma_f32_16x16x32_bf16 v[0:3], v[132:135], v[32:35], v[0:3]
	v_mfma_f32_16x16x32_bf16 v[4:7], v[132:135], v[36:39], v[4:7]
	ds_read_b128 v[32:35], v48 offset:128
	ds_read_b128 v[36:39], v48 offset:5504
	s_waitcnt lgkmcnt(1)
	v_mfma_f32_16x16x32_bf16 v[12:15], v[136:139], v[32:35], v[12:15]
	s_waitcnt lgkmcnt(0)
	v_mfma_f32_16x16x32_bf16 v[8:11], v[136:139], v[36:39], v[8:11]
	v_mfma_f32_16x16x32_bf16 v[20:23], v[140:143], v[32:35], v[20:23]
	v_mfma_f32_16x16x32_bf16 v[16:19], v[140:143], v[36:39], v[16:19]
	v_mfma_f32_16x16x32_bf16 v[28:31], v[144:147], v[32:35], v[28:31]
	v_mfma_f32_16x16x32_bf16 v[24:27], v[144:147], v[36:39], v[24:27]
	v_mfma_f32_16x16x32_bf16 v[0:3], v[148:151], v[32:35], v[0:3]
	v_mfma_f32_16x16x32_bf16 v[4:7], v[148:151], v[36:39], v[4:7]
	ds_read_b128 v[32:35], v48 offset:192
	ds_read_b128 v[36:39], v48 offset:5568
	s_waitcnt lgkmcnt(1)
	v_mfma_f32_16x16x32_bf16 v[12:15], v[152:155], v[32:35], v[12:15]
	s_waitcnt lgkmcnt(0)
	v_mfma_f32_16x16x32_bf16 v[8:11], v[152:155], v[36:39], v[8:11]
	v_mfma_f32_16x16x32_bf16 v[20:23], v[156:159], v[32:35], v[20:23]
	v_mfma_f32_16x16x32_bf16 v[16:19], v[156:159], v[36:39], v[16:19]
	v_mfma_f32_16x16x32_bf16 v[44:47], v[160:163], v[32:35], v[28:31]
	v_mfma_f32_16x16x32_bf16 v[40:43], v[160:163], v[36:39], v[24:27]
	s_nop 2
	v_mfma_f32_16x16x32_bf16 v[0:3], v[164:167], v[32:35], v[0:3]
	v_mfma_f32_16x16x32_bf16 v[32:35], v[164:167], v[36:39], v[4:7]
	ds_read_b128 v[36:39], v48 offset:256
	ds_read_b128 v[48:51], v48 offset:5632
	s_nop 0
	s_waitcnt lgkmcnt(1)
	v_mfma_f32_16x16x32_bf16 v[28:31], v[168:171], v[36:39], v[12:15]
	s_waitcnt lgkmcnt(0)
	v_mfma_f32_16x16x32_bf16 v[12:15], v[168:171], v[48:51], v[8:11]
	v_mov_b64_e32 v[54:55], s[0:1]
	v_mfma_f32_16x16x32_bf16 v[24:27], v[172:175], v[36:39], v[20:23]
	v_mfma_f32_16x16x32_bf16 v[8:11], v[172:175], v[48:51], v[16:19]
	v_mfma_f32_16x16x32_bf16 v[20:23], v[176:179], v[36:39], v[44:47]
	v_mfma_f32_16x16x32_bf16 v[4:7], v[176:179], v[48:51], v[40:43]
	s_nop 2
	v_mfma_f32_16x16x32_bf16 v[16:19], v[180:183], v[36:39], v[0:3]
	s_load_dwordx4 s[12:15], s[2:3], 0x90
	s_load_dwordx2 s[20:21], s[2:3], 0xa0
	s_waitcnt lgkmcnt(0)
; DI void rwkv_post_item(KA a, const int l, LAS unsigned char* lds, const int tile) {
;     ...
;     for (int rt = 0; rt < 2; ++rt) { const int tk = t0 + 32 * th + 16 * rt + fr;
;         float y[4][4], sy = 0.f, srk = 0.f;
; #pragma unroll
;         for (int ct = 0; ct < 4; ++ct) { const int c4 = hd * 64 + ct * 16 + 4 * fq; const size_t ro = (size_t)tk * 256 + c4; const f32x4 rk4 = *(const f32x4*)(rkw + c4);
;             const v2u yy = *(const v2u*)(H + (size_t)tk * HP + C_RR + c4), r2 = *(const v2u*)(Rr + ro), k2 = *(const v2u*)(Rk + ro);
;             const float y_[4] = {bflo(yy.x), bfhi(yy.x), bflo(yy.y), bfhi(yy.y)}, r_[4] = {bflo(r2.x), bfhi(r2.x), bflo(r2.y), bfhi(r2.y)}, k_[4] = {bflo(k2.x), bfhi(k2.x), bflo(k2.y), bfhi(k2.y)};
; #pragma unroll
;             for (int j = 0; j < 4; ++j) { y[ct][j] = y_[j]; sy += y_[j]; srk += r_[j] * k_[j] * rk4[j]; } }
;         sy += __shfl_xor(sy, 16); sy += __shfl_xor(sy, 32); srk += __shfl_xor(srk, 16); srk += __shfl_xor(srk, 32);
	s_add_u32 s16, s12, s22
	v_mfma_f32_16x16x32_bf16 v[0:3], v[180:183], v[48:51], v[32:35]
	v_or_b32_e32 v50, s19, v61
	v_lshl_or_b32 v48, v60, 2, v62
	v_ashrrev_i32_e32 v51, 31, v50
	v_and_b32_e32 v33, 64, v238
	v_xor_b32_e32 v32, 16, v238
	v_add_u32_e32 v33, 64, v33
	v_cmp_lt_i32_e32 vcc, v32, v33
	s_movk_i32 s19, 0x1c00
	v_ashrrev_i32_e32 v49, 31, v48
	v_cndmask_b32_e32 v32, v238, v32, vcc
	v_lshlrev_b32_e32 v76, 2, v32
	v_xor_b32_e32 v32, 32, v238
	v_cmp_lt_i32_e32 vcc, v32, v33
	v_mad_i64_i32 v[34:35], s[0:1], v50, s19, v[54:55]
	s_nop 0
	v_cndmask_b32_e32 v32, v238, v32, vcc
	v_lshlrev_b32_e32 v67, 2, v32
	v_lshlrev_b64 v[32:33], 8, v[50:51]
	v_lshl_add_u64 v[56:57], v[32:33], 0, v[48:49]
	v_lshlrev_b64 v[40:41], 1, v[48:49]
	v_lshl_add_u64 v[38:39], v[34:35], 0, v[40:41]
	v_lshlrev_b64 v[34:35], 1, v[56:57]
	v_lshl_add_u64 v[56:57], s[10:11], 0, v[34:35]
	v_lshl_add_u64 v[34:35], s[8:9], 0, v[34:35]
	s_addc_u32 s17, s13, s23
	v_lshlrev_b64 v[36:37], 2, v[48:49]
	global_load_dwordx2 v[52:53], v[38:39], off offset:2080
	v_lshl_add_u64 v[42:43], s[16:17], 0, v[36:37]
	global_load_dwordx2 v[56:57], v[56:57], off
	s_add_u32 s12, s14, s22
	global_load_dwordx2 v[34:35], v[34:35], off
	s_addc_u32 s13, s15, s23
	global_load_dwordx4 v[44:47], v[42:43], off
	s_add_u32 s14, s20, s22
	s_addc_u32 s15, s21, s23
	s_mov_b64 s[16:17], 0x4000200
	s_add_i32 s18, s18, s76
	s_cmpk_lt_i32 s18, 0x200
	s_waitcnt vmcnt(3)
	v_lshlrev_b32_e32 v82, 16, v52
	v_and_b32_e32 v83, 0xffff0000, v52
	s_waitcnt vmcnt(2)
	v_lshlrev_b32_e32 v58, 16, v56
	v_and_b32_e32 v56, 0xffff0000, v56
	s_waitcnt vmcnt(1)
	v_lshlrev_b32_e32 v60, 16, v34
	v_and_b32_e32 v34, 0xffff0000, v34
	v_mul_f32_e32 v58, v58, v60
	v_lshlrev_b32_e32 v59, 16, v57
	v_lshlrev_b32_e32 v61, 16, v35
	s_waitcnt vmcnt(0)
	v_fma_f32 v60, v44, v58, 0
	v_mul_f32_e32 v34, v56, v34
	v_and_b32_e32 v57, 0xffff0000, v57
	v_and_b32_e32 v35, 0xffff0000, v35
	v_fmac_f32_e32 v60, v45, v34
	v_mul_f32_e32 v34, v59, v61
	v_or_b32_e32 v56, 16, v48
	v_fmac_f32_e32 v60, v46, v34
	v_mul_f32_e32 v34, v57, v35
	v_ashrrev_i32_e32 v57, 31, v56
	v_fmac_f32_e32 v60, v47, v34
	v_lshl_add_u64 v[34:35], v[32:33], 0, v[56:57]
	v_lshlrev_b64 v[34:35], 1, v[34:35]
	v_lshl_add_u64 v[58:59], s[10:11], 0, v[34:35]
	v_lshl_add_u64 v[34:35], s[8:9], 0, v[34:35]
	global_load_dwordx4 v[44:47], v[42:43], off offset:64
	global_load_dwordx2 v[62:63], v[38:39], off offset:2112
	v_lshlrev_b32_e32 v80, 16, v53
	global_load_dwordx2 v[58:59], v[58:59], off
	v_and_b32_e32 v81, 0xffff0000, v53
	global_load_dwordx2 v[34:35], v[34:35], off
	s_waitcnt vmcnt(2)
	v_lshlrev_b32_e32 v94, 16, v62
	v_and_b32_e32 v95, 0xffff0000, v62
	s_waitcnt vmcnt(1)
	v_lshlrev_b32_e32 v61, 16, v58
	v_and_b32_e32 v58, 0xffff0000, v58
	s_waitcnt vmcnt(0)
	v_lshlrev_b32_e32 v64, 16, v34
	v_and_b32_e32 v34, 0xffff0000, v34
	v_mul_f32_e32 v61, v61, v64
	v_fmac_f32_e32 v60, v44, v61
	v_mul_f32_e32 v34, v58, v34
	v_fmac_f32_e32 v60, v45, v34
	v_and_b32_e32 v45, 0xffff0000, v59
	v_lshlrev_b32_e32 v44, 16, v59
	v_and_b32_e32 v59, 0xffff0000, v35
	v_lshlrev_b32_e32 v58, 16, v35
	v_pk_mul_f32 v[34:35], v[44:45], v[58:59]
	v_or_b32_e32 v58, 32, v48
	v_pk_mul_f32 v[34:35], v[46:47], v[34:35]
	v_ashrrev_i32_e32 v59, 31, v58
	v_add_f32_e32 v34, v34, v60
	v_add_f32_e32 v66, v35, v34
	v_lshl_add_u64 v[34:35], v[32:33], 0, v[58:59]
	v_lshlrev_b64 v[34:35], 1, v[34:35]
	v_lshl_add_u64 v[60:61], s[10:11], 0, v[34:35]
	v_lshl_add_u64 v[34:35], s[8:9], 0, v[34:35]
	global_load_dwordx4 v[44:47], v[42:43], off offset:128
	global_load_dwordx2 v[64:65], v[38:39], off offset:2144
	v_lshlrev_b32_e32 v90, 16, v63
	global_load_dwordx2 v[60:61], v[60:61], off
	v_and_b32_e32 v91, 0xffff0000, v63
	global_load_dwordx2 v[34:35], v[34:35], off
	s_waitcnt vmcnt(2)
	v_lshlrev_b32_e32 v62, 16, v64
	v_and_b32_e32 v63, 0xffff0000, v64
	s_waitcnt vmcnt(1)
	v_and_b32_e32 v69, 0xffff0000, v60
	v_lshlrev_b32_e32 v68, 16, v60
	s_waitcnt vmcnt(0)
	v_and_b32_e32 v71, 0xffff0000, v34
	v_lshlrev_b32_e32 v70, 16, v34
	v_pk_mul_f32 v[68:69], v[68:69], v[70:71]
	v_lshlrev_b32_e32 v60, 16, v35
	v_pk_mul_f32 v[44:45], v[44:45], v[68:69]
	s_nop 0
	v_add_f32_e32 v34, v66, v44
	v_add_f32_e32 v66, v45, v34
	v_and_b32_e32 v45, 0xffff0000, v61
	v_lshlrev_b32_e32 v44, 16, v61
	v_and_b32_e32 v61, 0xffff0000, v35
	v_pk_mul_f32 v[34:35], v[44:45], v[60:61]
	v_or_b32_e32 v60, 48, v48
	v_pk_mul_f32 v[34:35], v[46:47], v[34:35]
	v_ashrrev_i32_e32 v61, 31, v60
	v_add_f32_e32 v34, v34, v66
	v_lshl_add_u64 v[44:45], v[32:33], 0, v[60:61]
	v_add_f32_e32 v66, v35, v34
	global_load_dwordx4 v[32:35], v[42:43], off offset:192
	global_load_dwordx2 v[72:73], v[38:39], off offset:2176
	v_lshlrev_b64 v[38:39], 1, v[44:45]
	v_lshl_add_u64 v[44:45], s[10:11], 0, v[38:39]
	v_lshl_add_u64 v[38:39], s[8:9], 0, v[38:39]
	global_load_dwordx2 v[44:45], v[44:45], off
	s_waitcnt vmcnt(1)
	v_and_b32_e32 v86, 0xffff0000, v72
	global_load_dwordx2 v[38:39], v[38:39], off
	v_lshlrev_b32_e32 v87, 16, v72
	v_and_b32_e32 v72, 0xffff0000, v65
	s_waitcnt vmcnt(1)
	v_and_b32_e32 v47, 0xffff0000, v44
	v_lshlrev_b32_e32 v46, 16, v44
	s_waitcnt vmcnt(0)
	v_and_b32_e32 v69, 0xffff0000, v38
	v_lshlrev_b32_e32 v68, 16, v38
	v_pk_mul_f32 v[46:47], v[46:47], v[68:69]
	v_lshlrev_b32_e32 v44, 16, v39
	v_pk_mul_f32 v[32:33], v[32:33], v[46:47]
	v_lshl_add_u64 v[46:47], s[14:15], 0, v[36:37]
	v_add_f32_e32 v32, v66, v32
	v_add_f32_e32 v38, v33, v32
	v_and_b32_e32 v33, 0xffff0000, v45
	v_lshlrev_b32_e32 v32, 16, v45
	v_and_b32_e32 v45, 0xffff0000, v39
	v_pk_mul_f32 v[32:33], v[32:33], v[44:45]
	v_lshl_add_u64 v[44:45], s[12:13], 0, v[36:37]
	v_pk_mul_f32 v[32:33], v[34:35], v[32:33]
	s_mov_b32 s12, 0xf800000
	v_add_f32_e32 v32, v32, v38
	v_add_f32_e32 v32, v33, v32
	ds_bpermute_b32 v33, v76, v32
	global_load_dwordx4 v[36:39], v[46:47], off
	s_waitcnt lgkmcnt(0)
; DI unsigned pk2(float lo, float hi) { const f32x2 v = {lo, hi}; const bf16x2_t b = __builtin_convertvector(v, bf16x2_t); return __builtin_bit_cast(unsigned, b); }
; DI void rwkv_post_item(KA a, const int l, LAS unsigned char* lds, const int tile) {
;     ...
;         sy += __shfl_xor(sy, 16); sy += __shfl_xor(sy, 32); srk += __shfl_xor(srk, 16); srk += __shfl_xor(srk, 32);
;         const float mean = sy * (1.f / 64.f); float q = 0.f;
; #pragma unroll
;         for (int ct = 0; ct < 4; ++ct)
; #pragma unroll
;             for (int j = 0; j < 4; ++j) { const float d = y[ct][j] - mean; q += d * d; }
;         q += __shfl_xor(q, 16); q += __shfl_xor(q, 32);
;         const float rstd = 1.f / sqrtf(q * (1.f / 64.f) + 64e-5f);
; #pragma unroll
;         for (int ct = 0; ct < 4; ++ct) { const int c4 = hd * 64 + ct * 16 + 4 * fq; const size_t ro = (size_t)tk * 256 + c4; const f32x4 lw = *(const f32x4*)(lnw + c4), lb = *(const f32x4*)(lnb + c4);
;             const v2u v2 = *(const v2u*)(Rv + ro); const float v_[4] = {bflo(v2.x), bfhi(v2.x), bflo(v2.y), bfhi(v2.y)}; float o[4];
; #pragma unroll
;             for (int j = 0; j < 4; ++j) o[j] = ((y[ct][j] - mean) * rstd * lw[j] + lb[j] + srk * v_[j]) * accg[ct][rt][j];
;             v2u p; p.x = pk2(o[0], o[1]); p.y = pk2(o[2], o[3]); *(v2u*)(act + (size_t)tk * D + 256 + c4) = p; }
	v_add_f32_e32 v32, v32, v33
	ds_bpermute_b32 v33, v67, v32
	s_waitcnt lgkmcnt(0)
	v_add_f32_e32 v66, v32, v33
	v_lshlrev_b64 v[32:33], 9, v[50:51]
	v_lshl_add_u64 v[70:71], s[6:7], 0, v[32:33]
	v_lshl_add_u64 v[70:71], v[70:71], 0, v[40:41]
	global_load_dwordx2 v[78:79], v[70:71], off
	global_load_dwordx2 v[52:53], v[70:71], off offset:32
	global_load_dwordx2 v[100:101], v[70:71], off offset:64
	v_lshlrev_b64 v[32:33], 11, v[50:51]
	v_add_f32_e32 v51, 0, v82
	v_add_f32_e32 v51, v51, v83
	v_add_f32_e32 v51, v51, v80
	v_add_f32_e32 v51, v51, v81
	v_add_f32_e32 v51, v51, v94
	v_add_f32_e32 v51, v51, v95
	v_add_f32_e32 v51, v51, v90
	v_lshl_add_u64 v[32:33], s[4:5], 0, v[32:33]
	v_add_f32_e32 v51, v51, v91
	v_lshl_add_u64 v[68:69], v[32:33], 0, s[16:17]
	global_load_dwordx4 v[32:35], v[44:45], off
	global_load_dwordx4 v[128:131], v[44:45], off offset:64
	global_load_dwordx4 v[132:135], v[46:47], off offset:64
	global_load_dwordx4 v[136:139], v[44:45], off offset:128
	global_load_dwordx4 v[140:143], v[46:47], off offset:128
	global_load_dwordx4 v[144:147], v[44:45], off offset:192
	global_load_dwordx4 v[148:151], v[46:47], off offset:192
	v_add_f32_e32 v51, v51, v62
	v_add_f32_e32 v51, v51, v63
	v_lshl_add_u64 v[88:89], v[68:69], 0, v[40:41]
	s_waitcnt vmcnt(3)
	v_lshlrev_b32_e32 v74, 16, v79
	v_and_b32_e32 v75, 0xffff0000, v79
	v_lshlrev_b32_e32 v84, 16, v78
	v_and_b32_e32 v85, 0xffff0000, v78
	v_and_b32_e32 v78, 0xffff0000, v73
	v_lshlrev_b32_e32 v79, 16, v73
	v_lshlrev_b32_e32 v73, 16, v65
	v_add_f32_e32 v51, v51, v73
	v_add_f32_e32 v51, v51, v72
	v_add_f32_e32 v51, v51, v87
	v_add_f32_e32 v51, v51, v86
	v_add_f32_e32 v51, v51, v79
	v_add_f32_e32 v51, v51, v78
	ds_bpermute_b32 v64, v76, v51
	s_waitcnt vmcnt(2)
	v_lshlrev_b32_e32 v96, 16, v52
	v_and_b32_e32 v97, 0xffff0000, v52
	v_lshlrev_b32_e32 v92, 16, v53
	v_and_b32_e32 v93, 0xffff0000, v53
	s_waitcnt lgkmcnt(0)
	v_add_f32_e32 v51, v51, v64
	ds_bpermute_b32 v64, v67, v51
	v_lshlrev_b64 v[52:53], 1, v[56:57]
	v_lshl_add_u64 v[98:99], v[68:69], 0, v[52:53]
	s_waitcnt lgkmcnt(0)
	v_add_f32_e32 v51, v51, v64
	v_mul_f32_e32 v102, 0x3c800000, v51
	v_pk_add_f32 v[82:83], v[82:83], v[102:103] op_sel_hi:[1,0] neg_lo:[0,1] neg_hi:[0,1]
	v_pk_add_f32 v[80:81], v[80:81], v[102:103] op_sel_hi:[1,0] neg_lo:[0,1] neg_hi:[0,1]
	v_pk_mul_f32 v[104:105], v[82:83], v[82:83]
	v_pk_mul_f32 v[106:107], v[80:81], v[80:81]
	v_add_f32_e32 v51, v104, v105
	v_pk_add_f32 v[94:95], v[94:95], v[102:103] op_sel_hi:[1,0] neg_lo:[0,1] neg_hi:[0,1]
	v_add_f32_e32 v51, v106, v51
	v_pk_mul_f32 v[108:109], v[94:95], v[94:95]
	v_add_f32_e32 v51, v107, v51
	v_pk_add_f32 v[90:91], v[90:91], v[102:103] op_sel_hi:[1,0] neg_lo:[0,1] neg_hi:[0,1]
	v_add_f32_e32 v51, v108, v51
	v_pk_mul_f32 v[110:111], v[90:91], v[90:91]
	v_add_f32_e32 v51, v109, v51
	v_pk_add_f32 v[112:113], v[62:63], v[102:103] op_sel_hi:[1,0] neg_lo:[0,1] neg_hi:[0,1]
	v_add_f32_e32 v51, v110, v51
	v_pk_mul_f32 v[114:115], v[112:113], v[112:113]
	v_add_f32_e32 v51, v111, v51
	v_pk_add_f32 v[116:117], v[72:73], v[102:103] op_sel_hi:[1,0] neg_lo:[0,1] neg_hi:[0,1]
	v_add_f32_e32 v51, v114, v51
	v_pk_mul_f32 v[72:73], v[116:117], v[116:117]
	v_add_f32_e32 v51, v115, v51
	v_pk_add_f32 v[64:65], v[86:87], v[102:103] op_sel_hi:[1,0] neg_lo:[0,1] neg_hi:[0,1]
	v_add_f32_e32 v51, v73, v51
	v_pk_mul_f32 v[86:87], v[64:65], v[64:65]
	v_add_f32_e32 v51, v72, v51
	v_pk_add_f32 v[62:63], v[78:79], v[102:103] op_sel_hi:[1,0] neg_lo:[0,1] neg_hi:[0,1]
	v_add_f32_e32 v51, v87, v51
	v_pk_mul_f32 v[78:79], v[62:63], v[62:63]
	v_add_f32_e32 v51, v86, v51
	v_add_f32_e32 v51, v79, v51
	v_add_f32_e32 v51, v78, v51
	ds_bpermute_b32 v72, v76, v51
	s_waitcnt lgkmcnt(0)
	v_add_f32_e32 v51, v51, v72
	ds_bpermute_b32 v72, v67, v51
	s_waitcnt lgkmcnt(0)
	v_add_f32_e32 v51, v51, v72
	v_fmamk_f32 v51, v51, 0x3c800000, v236
	v_cmp_gt_f32_e32 vcc, s12, v51
	v_mul_f32_e32 v72, 0x4f800000, v51
	s_nop 0
	v_cndmask_b32_e32 v51, v51, v72, vcc
	v_sqrt_f32_e32 v72, v51
	s_nop 0
	v_add_u32_e32 v73, -1, v72
	v_fma_f32 v77, -v73, v72, v51
	v_cmp_ge_f32_e64 s[0:1], 0, v77
	v_add_u32_e32 v77, 1, v72
	s_nop 0
	v_cndmask_b32_e64 v73, v72, v73, s[0:1]
	v_fma_f32 v72, -v77, v72, v51
	v_cmp_lt_f32_e64 s[0:1], 0, v72
	s_nop 1
	v_cndmask_b32_e64 v72, v73, v77, s[0:1]
	v_mul_f32_e32 v73, 0x37800000, v72
	v_cndmask_b32_e32 v72, v72, v73, vcc
	v_cmp_class_f32_e32 vcc, v51, v234
	s_nop 1
	v_cndmask_b32_e32 v51, v72, v51, vcc
	v_div_scale_f32 v72, s[0:1], v51, v51, 1.0
	v_rcp_f32_e32 v73, v72
	s_nop 0
	v_fma_f32 v77, -v72, v73, 1.0
	v_fmac_f32_e32 v73, v77, v73
	v_div_scale_f32 v77, vcc, 1.0, v51, 1.0
	v_mul_f32_e32 v78, v77, v73
	v_fma_f32 v79, -v72, v78, v77
	v_fmac_f32_e32 v78, v79, v73
	v_fma_f32 v72, -v72, v78, v77
	v_div_fmas_f32 v72, v72, v73, v78
	v_div_fixup_f32 v72, v72, v51, 1.0
	v_pk_mul_f32 v[78:79], v[82:83], v[72:73] op_sel_hi:[1,0]
	s_waitcnt vmcnt(0)
	v_pk_fma_f32 v[32:33], v[32:33], v[78:79], v[36:37]
	v_pk_mul_f32 v[36:37], v[94:95], v[72:73] op_sel_hi:[1,0]
	v_pk_fma_f32 v[32:33], v[66:67], v[84:85], v[32:33] op_sel_hi:[0,1,1]
	v_pk_mul_f32 v[28:29], v[28:29], v[32:33]
	v_pk_mul_f32 v[32:33], v[80:81], v[72:73] op_sel_hi:[1,0]
	v_cvt_pk_bf16_f32 v28, v28, v29
	v_pk_fma_f32 v[32:33], v[34:35], v[32:33], v[38:39]
	s_nop 0
	v_pk_fma_f32 v[32:33], v[66:67], v[74:75], v[32:33] op_sel_hi:[0,1,1]
	v_pk_mul_f32 v[30:31], v[30:31], v[32:33]
	s_nop 0
	v_cvt_pk_bf16_f32 v29, v30, v31
	global_store_dwordx2 v[88:89], v[28:29], off
	s_nop 0
	s_waitcnt vmcnt(1)
; DI unsigned pk2(float lo, float hi) { const f32x2 v = {lo, hi}; const bf16x2_t b = __builtin_convertvector(v, bf16x2_t); return __builtin_bit_cast(unsigned, b); }
; DI void rwkv_post_item(KA a, const int l, LAS unsigned char* lds, const int tile) {
;     ...
;     for (int rt = 0; rt < 2; ++rt) { const int tk = t0 + 32 * th + 16 * rt + fr;
;         float y[4][4], sy = 0.f, srk = 0.f;
; #pragma unroll
;         for (int ct = 0; ct < 4; ++ct) { const int c4 = hd * 64 + ct * 16 + 4 * fq; const size_t ro = (size_t)tk * 256 + c4; const f32x4 rk4 = *(const f32x4*)(rkw + c4);
;             const v2u yy = *(const v2u*)(H + (size_t)tk * HP + C_RR + c4), r2 = *(const v2u*)(Rr + ro), k2 = *(const v2u*)(Rk + ro);
;             const float y_[4] = {bflo(yy.x), bfhi(yy.x), bflo(yy.y), bfhi(yy.y)}, r_[4] = {bflo(r2.x), bfhi(r2.x), bflo(r2.y), bfhi(r2.y)}, k_[4] = {bflo(k2.x), bfhi(k2.x), bflo(k2.y), bfhi(k2.y)};
; #pragma unroll
;             for (int j = 0; j < 4; ++j) { y[ct][j] = y_[j]; sy += y_[j]; srk += r_[j] * k_[j] * rk4[j]; } }
;         sy += __shfl_xor(sy, 16); sy += __shfl_xor(sy, 32); srk += __shfl_xor(srk, 16); srk += __shfl_xor(srk, 32);
;         const float mean = sy * (1.f / 64.f); float q = 0.f;
; #pragma unroll
;         for (int ct = 0; ct < 4; ++ct)
; #pragma unroll
;             for (int j = 0; j < 4; ++j) { const float d = y[ct][j] - mean; q += d * d; }
;         q += __shfl_xor(q, 16); q += __shfl_xor(q, 32);
;         const float rstd = 1.f / sqrtf(q * (1.f / 64.f) + 64e-5f);
; #pragma unroll
;         for (int ct = 0; ct < 4; ++ct) { const int c4 = hd * 64 + ct * 16 + 4 * fq; const size_t ro = (size_t)tk * 256 + c4; const f32x4 lw = *(const f32x4*)(lnw + c4), lb = *(const f32x4*)(lnb + c4);
;             const v2u v2 = *(const v2u*)(Rv + ro); const float v_[4] = {bflo(v2.x), bfhi(v2.x), bflo(v2.y), bfhi(v2.y)}; float o[4];
; #pragma unroll
;             for (int j = 0; j < 4; ++j) o[j] = ((y[ct][j] - mean) * rstd * lw[j] + lb[j] + srk * v_[j]) * accg[ct][rt][j];
;             v2u p; p.x = pk2(o[0], o[1]); p.y = pk2(o[2], o[3]); *(v2u*)(act + (size_t)tk * D + 256 + c4) = p; }
	v_pk_fma_f32 v[28:29], v[128:129], v[36:37], v[132:133]
	s_nop 0
	v_pk_fma_f32 v[28:29], v[66:67], v[96:97], v[28:29] op_sel_hi:[0,1,1]
	v_pk_mul_f32 v[24:25], v[24:25], v[28:29]
	v_pk_mul_f32 v[28:29], v[90:91], v[72:73] op_sel_hi:[1,0]
	v_cvt_pk_bf16_f32 v24, v24, v25
	v_pk_fma_f32 v[28:29], v[130:131], v[28:29], v[134:135]
	v_pk_mul_f32 v[34:35], v[112:113], v[72:73] op_sel_hi:[1,0]
	v_pk_fma_f32 v[28:29], v[66:67], v[92:93], v[28:29] op_sel_hi:[0,1,1]
	v_pk_mul_f32 v[26:27], v[26:27], v[28:29]
	v_lshlrev_b32_e32 v32, 16, v100
	v_cvt_pk_bf16_f32 v25, v26, v27
	global_store_dwordx2 v[98:99], v[24:25], off
	s_nop 0
	v_and_b32_e32 v33, 0xffff0000, v100
	s_waitcnt vmcnt(1)
	v_pk_fma_f32 v[24:25], v[136:137], v[34:35], v[140:141]
	s_nop 0
	v_pk_fma_f32 v[24:25], v[66:67], v[32:33], v[24:25] op_sel_hi:[0,1,1]
	v_pk_mul_f32 v[28:29], v[116:117], v[72:73] op_sel_hi:[1,0]
	v_pk_mul_f32 v[20:21], v[20:21], v[24:25]
	v_lshlrev_b32_e32 v24, 16, v101
	v_and_b32_e32 v25, 0xffff0000, v101
	v_pk_fma_f32 v[26:27], v[138:139], v[28:29], v[142:143] op_sel:[0,1,0] op_sel_hi:[1,0,1]
	v_lshlrev_b64 v[28:29], 1, v[58:59]
	v_pk_fma_f32 v[24:25], v[66:67], v[24:25], v[26:27] op_sel_hi:[0,1,1]
	v_pk_mul_f32 v[22:23], v[22:23], v[24:25]
	v_cvt_pk_bf16_f32 v20, v20, v21
	v_cvt_pk_bf16_f32 v21, v22, v23
	v_lshl_add_u64 v[22:23], v[68:69], 0, v[28:29]
	global_store_dwordx2 v[22:23], v[20:21], off
	s_nop 0
	global_load_dwordx2 v[30:31], v[70:71], off offset:96
	v_pk_mul_f32 v[34:35], v[64:65], v[72:73] op_sel_hi:[1,0]
	s_waitcnt vmcnt(0)
	v_lshlrev_b32_e32 v32, 16, v30
	v_and_b32_e32 v33, 0xffff0000, v30
	v_pk_fma_f32 v[20:21], v[144:145], v[34:35], v[148:149] op_sel:[0,1,0] op_sel_hi:[1,0,1]
	v_pk_mul_f32 v[24:25], v[62:63], v[72:73] op_sel_hi:[1,0]
	v_pk_fma_f32 v[20:21], v[66:67], v[32:33], v[20:21] op_sel_hi:[0,1,1]
	v_pk_mul_f32 v[16:17], v[16:17], v[20:21]
	v_lshlrev_b32_e32 v20, 16, v31
	v_and_b32_e32 v21, 0xffff0000, v31
	v_pk_fma_f32 v[22:23], v[146:147], v[24:25], v[150:151] op_sel:[0,1,0] op_sel_hi:[1,0,1]
	v_lshlrev_b64 v[24:25], 1, v[60:61]
	v_pk_fma_f32 v[20:21], v[66:67], v[20:21], v[22:23] op_sel_hi:[0,1,1]
	v_pk_mul_f32 v[18:19], v[18:19], v[20:21]
	v_cvt_pk_bf16_f32 v16, v16, v17
	v_cvt_pk_bf16_f32 v17, v18, v19
	v_lshl_add_u64 v[18:19], v[68:69], 0, v[24:25]
	global_store_dwordx2 v[18:19], v[16:17], off
	v_or_b32_e32 v16, 16, v50
	v_ashrrev_i32_e32 v17, 31, v16
	v_lshlrev_b64 v[18:19], 8, v[16:17]
	v_lshl_add_u64 v[22:23], v[18:19], 0, v[48:49]
	v_mad_i64_i32 v[20:21], s[0:1], v16, s19, v[54:55]
	v_lshlrev_b64 v[22:23], 1, v[22:23]
	v_lshl_add_u64 v[20:21], v[20:21], 0, v[40:41]
	v_lshl_add_u64 v[26:27], s[10:11], 0, v[22:23]
	v_lshl_add_u64 v[22:23], s[8:9], 0, v[22:23]
	global_load_dwordx2 v[32:33], v[20:21], off offset:2080
	global_load_dwordx4 v[34:37], v[42:43], off
	s_nop 0
	global_load_dwordx2 v[26:27], v[26:27], off
	s_nop 0
	global_load_dwordx2 v[22:23], v[22:23], off
	s_waitcnt vmcnt(1)
	v_lshlrev_b32_e32 v30, 16, v26
	v_and_b32_e32 v26, 0xffff0000, v26
	s_waitcnt vmcnt(0)
	v_lshlrev_b32_e32 v38, 16, v22
	v_and_b32_e32 v22, 0xffff0000, v22
	v_mul_f32_e32 v30, v30, v38
	v_lshlrev_b32_e32 v31, 16, v27
	v_lshlrev_b32_e32 v39, 16, v23
	v_fma_f32 v48, v34, v30, 0
	v_mul_f32_e32 v22, v26, v22
	v_and_b32_e32 v27, 0xffff0000, v27
	v_and_b32_e32 v23, 0xffff0000, v23
	v_fmac_f32_e32 v48, v35, v22
	v_mul_f32_e32 v22, v31, v39
	v_fmac_f32_e32 v48, v36, v22
	v_mul_f32_e32 v22, v27, v23
	v_fmac_f32_e32 v48, v37, v22
	v_lshl_add_u64 v[22:23], v[18:19], 0, v[56:57]
	v_lshlrev_b64 v[22:23], 1, v[22:23]
	v_lshl_add_u64 v[26:27], s[10:11], 0, v[22:23]
	v_lshl_add_u64 v[22:23], s[8:9], 0, v[22:23]
	global_load_dwordx4 v[36:39], v[42:43], off offset:64
	global_load_dwordx2 v[34:35], v[20:21], off offset:2112
	v_lshlrev_b32_e32 v56, 16, v32
	global_load_dwordx2 v[26:27], v[26:27], off
	v_and_b32_e32 v57, 0xffff0000, v32
	global_load_dwordx2 v[22:23], v[22:23], off
	s_waitcnt vmcnt(2)
	v_lshlrev_b32_e32 v68, 16, v34
	v_and_b32_e32 v69, 0xffff0000, v34
	s_waitcnt vmcnt(1)
	v_lshlrev_b32_e32 v30, 16, v26
	v_and_b32_e32 v26, 0xffff0000, v26
	s_waitcnt vmcnt(0)
	v_lshlrev_b32_e32 v31, 16, v22
	v_and_b32_e32 v22, 0xffff0000, v22
	v_mul_f32_e32 v30, v30, v31
	v_fmac_f32_e32 v48, v36, v30
	v_mul_f32_e32 v22, v26, v22
	v_and_b32_e32 v31, 0xffff0000, v27
	v_lshlrev_b32_e32 v30, 16, v27
	v_and_b32_e32 v27, 0xffff0000, v23
	v_lshlrev_b32_e32 v26, 16, v23
	v_fmac_f32_e32 v48, v37, v22
	v_pk_mul_f32 v[22:23], v[30:31], v[26:27]
	v_lshlrev_b32_e32 v62, 16, v35
	v_pk_mul_f32 v[22:23], v[38:39], v[22:23]
	v_and_b32_e32 v63, 0xffff0000, v35
	v_add_f32_e32 v22, v22, v48
	v_add_f32_e32 v54, v23, v22
	v_lshl_add_u64 v[22:23], v[18:19], 0, v[58:59]
	v_lshlrev_b64 v[22:23], 1, v[22:23]
	v_lshl_add_u64 v[26:27], s[10:11], 0, v[22:23]
	v_lshl_add_u64 v[22:23], s[8:9], 0, v[22:23]
	global_load_dwordx4 v[48:51], v[42:43], off offset:128
	global_load_dwordx2 v[38:39], v[20:21], off offset:2144
	v_lshl_add_u64 v[18:19], v[18:19], 0, v[60:61]
	global_load_dwordx2 v[26:27], v[26:27], off
	v_lshlrev_b64 v[18:19], 1, v[18:19]
	global_load_dwordx2 v[22:23], v[22:23], off
	s_waitcnt vmcnt(2)
	v_lshlrev_b32_e32 v34, 16, v38
	v_and_b32_e32 v35, 0xffff0000, v38
	s_waitcnt vmcnt(1)
	v_and_b32_e32 v31, 0xffff0000, v26
	v_lshlrev_b32_e32 v30, 16, v26
	s_waitcnt vmcnt(0)
; DI unsigned pk2(float lo, float hi) { const f32x2 v = {lo, hi}; const bf16x2_t b = __builtin_convertvector(v, bf16x2_t); return __builtin_bit_cast(unsigned, b); }
; DI void rwkv_post_item(KA a, const int l, LAS unsigned char* lds, const int tile) {
;     ...
;         for (int ct = 0; ct < 4; ++ct) { const int c4 = hd * 64 + ct * 16 + 4 * fq; const size_t ro = (size_t)tk * 256 + c4; const f32x4 rk4 = *(const f32x4*)(rkw + c4);
;             const v2u yy = *(const v2u*)(H + (size_t)tk * HP + C_RR + c4), r2 = *(const v2u*)(Rr + ro), k2 = *(const v2u*)(Rk + ro);
;             const float y_[4] = {bflo(yy.x), bfhi(yy.x), bflo(yy.y), bfhi(yy.y)}, r_[4] = {bflo(r2.x), bfhi(r2.x), bflo(r2.y), bfhi(r2.y)}, k_[4] = {bflo(k2.x), bfhi(k2.x), bflo(k2.y), bfhi(k2.y)};
; #pragma unroll
;             for (int j = 0; j < 4; ++j) { y[ct][j] = y_[j]; sy += y_[j]; srk += r_[j] * k_[j] * rk4[j]; } }
;         sy += __shfl_xor(sy, 16); sy += __shfl_xor(sy, 32); srk += __shfl_xor(srk, 16); srk += __shfl_xor(srk, 32);
;         const float mean = sy * (1.f / 64.f); float q = 0.f;
; #pragma unroll
;         for (int ct = 0; ct < 4; ++ct)
; #pragma unroll
;             for (int j = 0; j < 4; ++j) { const float d = y[ct][j] - mean; q += d * d; }
;         q += __shfl_xor(q, 16); q += __shfl_xor(q, 32);
;         const float rstd = 1.f / sqrtf(q * (1.f / 64.f) + 64e-5f);
; #pragma unroll
;         for (int ct = 0; ct < 4; ++ct) { const int c4 = hd * 64 + ct * 16 + 4 * fq; const size_t ro = (size_t)tk * 256 + c4; const f32x4 lw = *(const f32x4*)(lnw + c4), lb = *(const f32x4*)(lnb + c4);
;             const v2u v2 = *(const v2u*)(Rv + ro); const float v_[4] = {bflo(v2.x), bfhi(v2.x), bflo(v2.y), bfhi(v2.y)}; float o[4];
; #pragma unroll
;             for (int j = 0; j < 4; ++j) o[j] = ((y[ct][j] - mean) * rstd * lw[j] + lb[j] + srk * v_[j]) * accg[ct][rt][j];
;             v2u p; p.x = pk2(o[0], o[1]); p.y = pk2(o[2], o[3]); *(v2u*)(act + (size_t)tk * D + 256 + c4) = p; }
	v_and_b32_e32 v37, 0xffff0000, v22
	v_lshlrev_b32_e32 v36, 16, v22
	v_pk_mul_f32 v[30:31], v[30:31], v[36:37]
	v_lshlrev_b32_e32 v26, 16, v23
	v_pk_mul_f32 v[30:31], v[48:49], v[30:31]
	s_nop 0
	v_add_f32_e32 v22, v54, v30
	v_add_f32_e32 v36, v31, v22
	v_and_b32_e32 v31, 0xffff0000, v27
	v_lshlrev_b32_e32 v30, 16, v27
	v_and_b32_e32 v27, 0xffff0000, v23
	v_pk_mul_f32 v[22:23], v[30:31], v[26:27]
	v_add_f32_e32 v31, 0, v56
	v_pk_mul_f32 v[22:23], v[50:51], v[22:23]
	global_load_dwordx4 v[48:51], v[42:43], off offset:192
	s_nop 0
	global_load_dwordx2 v[42:43], v[20:21], off offset:2176
	v_lshl_add_u64 v[20:21], s[10:11], 0, v[18:19]
	v_lshl_add_u64 v[18:19], s[8:9], 0, v[18:19]
	global_load_dwordx2 v[20:21], v[20:21], off
	v_add_f32_e32 v22, v22, v36
	global_load_dwordx2 v[18:19], v[18:19], off
	v_add_f32_e32 v30, v23, v22
	v_add_f32_e32 v31, v31, v57
	s_waitcnt vmcnt(2)
	v_and_b32_e32 v32, 0xffff0000, v43
	s_waitcnt vmcnt(1)
	v_and_b32_e32 v23, 0xffff0000, v20
	v_lshlrev_b32_e32 v22, 16, v20
	s_waitcnt vmcnt(0)
	v_and_b32_e32 v27, 0xffff0000, v18
	v_lshlrev_b32_e32 v26, 16, v18
	v_pk_mul_f32 v[22:23], v[22:23], v[26:27]
	v_lshlrev_b32_e32 v20, 16, v19
	v_pk_mul_f32 v[22:23], v[48:49], v[22:23]
	v_lshlrev_b32_e32 v48, 16, v33
	v_add_f32_e32 v18, v30, v22
	v_add_f32_e32 v26, v23, v18
	v_and_b32_e32 v23, 0xffff0000, v21
	v_lshlrev_b32_e32 v22, 16, v21
	v_and_b32_e32 v21, 0xffff0000, v19
	v_pk_mul_f32 v[18:19], v[22:23], v[20:21]
	v_and_b32_e32 v49, 0xffff0000, v33
	v_pk_mul_f32 v[18:19], v[50:51], v[18:19]
	v_add_f32_e32 v31, v31, v48
	v_add_f32_e32 v18, v18, v26
	v_add_f32_e32 v18, v19, v18
	ds_bpermute_b32 v19, v76, v18
	v_add_f32_e32 v31, v31, v49
	v_add_f32_e32 v31, v31, v68
	v_add_f32_e32 v31, v31, v69
	v_add_f32_e32 v31, v31, v62
	s_waitcnt lgkmcnt(0)
	v_add_f32_e32 v18, v18, v19
	ds_bpermute_b32 v19, v67, v18
	v_add_f32_e32 v31, v31, v63
	v_add_f32_e32 v31, v31, v34
	v_lshlrev_b32_e32 v33, 16, v43
	v_lshlrev_b32_e32 v43, 16, v39
	s_waitcnt lgkmcnt(0)
	v_add_f32_e32 v30, v18, v19
	v_lshlrev_b64 v[18:19], 9, v[16:17]
	v_lshl_add_u64 v[36:37], s[6:7], 0, v[18:19]
	v_lshlrev_b64 v[16:17], 11, v[16:17]
	v_lshl_add_u64 v[16:17], s[4:5], 0, v[16:17]
	v_lshl_add_u64 v[36:37], v[36:37], 0, v[40:41]
	v_lshl_add_u64 v[26:27], v[16:17], 0, s[16:17]
	global_load_dwordx4 v[16:19], v[44:45], off
	global_load_dwordx4 v[20:23], v[46:47], off
	global_load_dwordx4 v[152:155], v[44:45], off offset:64
	global_load_dwordx4 v[156:159], v[46:47], off offset:64
	global_load_dwordx4 v[160:163], v[44:45], off offset:128
	global_load_dwordx4 v[164:167], v[46:47], off offset:128
	global_load_dwordx4 v[168:171], v[44:45], off offset:192
	global_load_dwordx4 v[172:175], v[46:47], off offset:192
	global_load_dwordx2 v[54:55], v[36:37], off
	global_load_dwordx2 v[60:61], v[36:37], off offset:32
	v_add_f32_e32 v31, v31, v35
	v_add_f32_e32 v31, v31, v43
	v_lshl_add_u64 v[40:41], v[26:27], 0, v[40:41]
	v_lshl_add_u64 v[52:53], v[26:27], 0, v[52:53]
	s_waitcnt vmcnt(1)
	v_lshlrev_b32_e32 v50, 16, v55
	v_and_b32_e32 v51, 0xffff0000, v55
	v_lshlrev_b32_e32 v58, 16, v54
	v_and_b32_e32 v59, 0xffff0000, v54
	v_and_b32_e32 v54, 0xffff0000, v42
	v_lshlrev_b32_e32 v55, 16, v42
	v_and_b32_e32 v42, 0xffff0000, v39
	v_add_f32_e32 v31, v31, v42
	v_add_f32_e32 v31, v31, v55
	v_add_f32_e32 v31, v31, v54
	v_add_f32_e32 v31, v31, v33
	v_add_f32_e32 v31, v31, v32
	ds_bpermute_b32 v38, v76, v31
	s_waitcnt vmcnt(0)
	v_lshlrev_b32_e32 v64, 16, v61
	v_and_b32_e32 v65, 0xffff0000, v61
	v_lshlrev_b32_e32 v70, 16, v60
	v_and_b32_e32 v71, 0xffff0000, v60
	s_waitcnt lgkmcnt(0)
	v_add_f32_e32 v31, v31, v38
	ds_bpermute_b32 v38, v67, v31
	global_load_dwordx2 v[60:61], v[36:37], off offset:64
	s_waitcnt lgkmcnt(0)
	v_add_f32_e32 v31, v31, v38
	v_mul_f32_e32 v38, 0x3c800000, v31
	v_pk_add_f32 v[56:57], v[56:57], v[38:39] op_sel_hi:[1,0] neg_lo:[0,1] neg_hi:[0,1]
	v_pk_add_f32 v[48:49], v[48:49], v[38:39] op_sel_hi:[1,0] neg_lo:[0,1] neg_hi:[0,1]
	v_pk_mul_f32 v[72:73], v[56:57], v[56:57]
	v_pk_mul_f32 v[74:75], v[48:49], v[48:49]
	v_add_f32_e32 v31, v72, v73
	v_pk_add_f32 v[68:69], v[68:69], v[38:39] op_sel_hi:[1,0] neg_lo:[0,1] neg_hi:[0,1]
	v_add_f32_e32 v31, v74, v31
	v_pk_mul_f32 v[78:79], v[68:69], v[68:69]
	v_add_f32_e32 v31, v75, v31
	v_pk_add_f32 v[62:63], v[62:63], v[38:39] op_sel_hi:[1,0] neg_lo:[0,1] neg_hi:[0,1]
	v_add_f32_e32 v31, v78, v31
	v_pk_mul_f32 v[80:81], v[62:63], v[62:63]
	v_add_f32_e32 v31, v79, v31
	v_pk_add_f32 v[82:83], v[34:35], v[38:39] op_sel_hi:[1,0] neg_lo:[0,1] neg_hi:[0,1]
	v_add_f32_e32 v31, v80, v31
	v_pk_mul_f32 v[84:85], v[82:83], v[82:83]
	v_add_f32_e32 v31, v81, v31
	v_pk_add_f32 v[42:43], v[42:43], v[38:39] op_sel_hi:[1,0] neg_lo:[0,1] neg_hi:[0,1]
	v_add_f32_e32 v31, v84, v31
	v_pk_mul_f32 v[86:87], v[42:43], v[42:43]
	v_add_f32_e32 v31, v85, v31
	v_pk_add_f32 v[34:35], v[54:55], v[38:39] op_sel_hi:[1,0] neg_lo:[0,1] neg_hi:[0,1]
	v_add_f32_e32 v31, v87, v31
	v_pk_mul_f32 v[54:55], v[34:35], v[34:35]
	v_add_f32_e32 v31, v86, v31
	v_pk_add_f32 v[32:33], v[32:33], v[38:39] op_sel_hi:[1,0] neg_lo:[0,1] neg_hi:[0,1]
	v_add_f32_e32 v31, v55, v31
	v_pk_mul_f32 v[38:39], v[32:33], v[32:33]
	v_add_f32_e32 v31, v54, v31
	v_add_f32_e32 v31, v39, v31
	v_add_f32_e32 v31, v38, v31
	ds_bpermute_b32 v38, v76, v31
	s_waitcnt lgkmcnt(0)
; DI unsigned pk2(float lo, float hi) { const f32x2 v = {lo, hi}; const bf16x2_t b = __builtin_convertvector(v, bf16x2_t); return __builtin_bit_cast(unsigned, b); }
; DI void rwkv_post_item(KA a, const int l, LAS unsigned char* lds, const int tile) {
;     ...
;         const float rstd = 1.f / sqrtf(q * (1.f / 64.f) + 64e-5f);
; #pragma unroll
;         for (int ct = 0; ct < 4; ++ct) { const int c4 = hd * 64 + ct * 16 + 4 * fq; const size_t ro = (size_t)tk * 256 + c4; const f32x4 lw = *(const f32x4*)(lnw + c4), lb = *(const f32x4*)(lnb + c4);
;             const v2u v2 = *(const v2u*)(Rv + ro); const float v_[4] = {bflo(v2.x), bfhi(v2.x), bflo(v2.y), bfhi(v2.y)}; float o[4];
; #pragma unroll
;             for (int j = 0; j < 4; ++j) o[j] = ((y[ct][j] - mean) * rstd * lw[j] + lb[j] + srk * v_[j]) * accg[ct][rt][j];
;             v2u p; p.x = pk2(o[0], o[1]); p.y = pk2(o[2], o[3]); *(v2u*)(act + (size_t)tk * D + 256 + c4) = p; }
	v_add_f32_e32 v31, v31, v38
	ds_bpermute_b32 v38, v67, v31
	s_waitcnt lgkmcnt(0)
	v_add_f32_e32 v31, v31, v38
	v_fmamk_f32 v31, v31, 0x3c800000, v236
	v_cmp_gt_f32_e32 vcc, s12, v31
	v_mul_f32_e32 v38, 0x4f800000, v31
	s_nop 0
	v_cndmask_b32_e32 v31, v31, v38, vcc
	v_sqrt_f32_e32 v38, v31
	s_nop 0
	v_add_u32_e32 v39, -1, v38
	v_fma_f32 v54, -v39, v38, v31
	v_cmp_ge_f32_e64 s[0:1], 0, v54
	v_add_u32_e32 v54, 1, v38
	s_nop 0
	v_cndmask_b32_e64 v39, v38, v39, s[0:1]
	v_fma_f32 v38, -v54, v38, v31
	v_cmp_lt_f32_e64 s[0:1], 0, v38
	s_nop 1
	v_cndmask_b32_e64 v38, v39, v54, s[0:1]
	v_mul_f32_e32 v39, 0x37800000, v38
	v_cndmask_b32_e32 v38, v38, v39, vcc
	v_cmp_class_f32_e32 vcc, v31, v234
	s_nop 1
	v_cndmask_b32_e32 v31, v38, v31, vcc
	v_div_scale_f32 v38, s[0:1], v31, v31, 1.0
	v_rcp_f32_e32 v39, v38
	s_nop 0
	v_fma_f32 v54, -v38, v39, 1.0
	v_fmac_f32_e32 v39, v54, v39
	v_div_scale_f32 v54, vcc, 1.0, v31, 1.0
	v_mul_f32_e32 v55, v54, v39
	v_fma_f32 v66, -v38, v55, v54
	v_fmac_f32_e32 v55, v66, v39
	v_fma_f32 v38, -v38, v55, v54
	v_div_fmas_f32 v38, v38, v39, v55
	v_div_fixup_f32 v38, v38, v31, 1.0
	v_pk_mul_f32 v[54:55], v[56:57], v[38:39] op_sel_hi:[1,0]
	s_nop 0
	v_pk_fma_f32 v[16:17], v[16:17], v[54:55], v[20:21]
	v_pk_mul_f32 v[20:21], v[68:69], v[38:39] op_sel_hi:[1,0]
	v_pk_fma_f32 v[16:17], v[30:31], v[58:59], v[16:17] op_sel_hi:[0,1,1]
	v_pk_mul_f32 v[12:13], v[12:13], v[16:17]
	v_pk_mul_f32 v[16:17], v[48:49], v[38:39] op_sel_hi:[1,0]
	v_cvt_pk_bf16_f32 v12, v12, v13
	v_pk_fma_f32 v[16:17], v[18:19], v[16:17], v[22:23]
	s_nop 0
	v_pk_fma_f32 v[16:17], v[30:31], v[50:51], v[16:17] op_sel_hi:[0,1,1]
	v_pk_mul_f32 v[14:15], v[14:15], v[16:17]
	s_nop 0
	v_cvt_pk_bf16_f32 v13, v14, v15
	global_store_dwordx2 v[40:41], v[12:13], off
	s_nop 0
	s_waitcnt vmcnt(1)
	v_pk_fma_f32 v[12:13], v[152:153], v[20:21], v[156:157]
	s_nop 0
	v_pk_fma_f32 v[12:13], v[30:31], v[70:71], v[12:13] op_sel_hi:[0,1,1]
	v_pk_mul_f32 v[8:9], v[8:9], v[12:13]
	v_pk_mul_f32 v[12:13], v[62:63], v[38:39] op_sel_hi:[1,0]
	v_cvt_pk_bf16_f32 v8, v8, v9
	v_pk_fma_f32 v[12:13], v[154:155], v[12:13], v[158:159]
	v_pk_mul_f32 v[18:19], v[82:83], v[38:39] op_sel_hi:[1,0]
	v_pk_fma_f32 v[12:13], v[30:31], v[64:65], v[12:13] op_sel_hi:[0,1,1]
	v_pk_mul_f32 v[10:11], v[10:11], v[12:13]
	v_lshlrev_b32_e32 v16, 16, v60
	v_cvt_pk_bf16_f32 v9, v10, v11
	global_store_dwordx2 v[52:53], v[8:9], off
	s_nop 0
	v_and_b32_e32 v17, 0xffff0000, v60
	s_waitcnt vmcnt(1)
	v_pk_fma_f32 v[8:9], v[160:161], v[18:19], v[164:165]
	s_nop 0
	v_pk_fma_f32 v[8:9], v[30:31], v[16:17], v[8:9] op_sel_hi:[0,1,1]
	v_pk_mul_f32 v[12:13], v[42:43], v[38:39] op_sel_hi:[1,0]
	v_pk_mul_f32 v[4:5], v[4:5], v[8:9]
	v_lshlrev_b32_e32 v8, 16, v61
	v_and_b32_e32 v9, 0xffff0000, v61
	v_pk_fma_f32 v[10:11], v[162:163], v[12:13], v[166:167] op_sel:[0,1,0] op_sel_hi:[1,0,1]
	v_cvt_pk_bf16_f32 v4, v4, v5
	v_pk_fma_f32 v[8:9], v[30:31], v[8:9], v[10:11] op_sel_hi:[0,1,1]
	v_pk_mul_f32 v[6:7], v[6:7], v[8:9]
	v_pk_mul_f32 v[16:17], v[34:35], v[38:39] op_sel_hi:[1,0]
	v_cvt_pk_bf16_f32 v5, v6, v7
	v_lshl_add_u64 v[6:7], v[26:27], 0, v[28:29]
	global_store_dwordx2 v[6:7], v[4:5], off
	s_nop 0
	global_load_dwordx2 v[12:13], v[36:37], off offset:96
	s_waitcnt vmcnt(1)
	v_pk_fma_f32 v[4:5], v[168:169], v[16:17], v[172:173] op_sel:[0,1,0] op_sel_hi:[1,0,1]
	s_waitcnt vmcnt(0)
	v_lshlrev_b32_e32 v14, 16, v12
	v_and_b32_e32 v15, 0xffff0000, v12
	v_pk_fma_f32 v[4:5], v[30:31], v[14:15], v[4:5] op_sel_hi:[0,1,1]
	v_pk_mul_f32 v[8:9], v[32:33], v[38:39] op_sel_hi:[1,0]
	v_pk_mul_f32 v[0:1], v[0:1], v[4:5]
	v_lshlrev_b32_e32 v4, 16, v13
	v_and_b32_e32 v5, 0xffff0000, v13
	v_pk_fma_f32 v[6:7], v[170:171], v[8:9], v[174:175] op_sel:[0,1,0] op_sel_hi:[1,0,1]
	v_cvt_pk_bf16_f32 v0, v0, v1
	v_pk_fma_f32 v[4:5], v[30:31], v[4:5], v[6:7] op_sel_hi:[0,1,1]
	v_pk_mul_f32 v[2:3], v[2:3], v[4:5]
	s_nop 0
	v_cvt_pk_bf16_f32 v1, v2, v3
	v_lshl_add_u64 v[2:3], v[26:27], 0, v[24:25]
	global_store_dwordx2 v[2:3], v[0:1], off
	s_cbranch_scc0 .LBB0_986
